# softmax row-max: dropped redundant self-max canonicalisation ops (22 sites), same values
# baseline (speedup 1.0000x reference)
.LBB0_448:
	s_nop 9
	v_max_f32_e32 v0, v66, v67
	v_max3_f32 v0, v0, v68, v69
	v_max3_f32 v0, v0, v70, v71
	v_max3_f32 v0, v0, v72, v73
	v_max3_f32 v0, v0, v74, v75
	v_max3_f32 v0, v0, v76, v77
	v_max3_f32 v0, v0, v78, v79
	v_max3_f32 v0, v0, v80, v81
	v_mov_b32_e32 v196, v0
	s_nop 1
	v_permlane32_swap_b32_e32 v0, v196
	v_max_f32_e32 v0, v0, v196
	v_mul_f32_e32 v0, 0x3e38aa3b, v0
	v_max_f32_e32 v0, v195, v0
	v_sub_f32_e32 v196, v0, v195
	v_cmp_lt_f32_e32 vcc, s67, v196
	s_cbranch_vccz .LBB0_450
	v_sub_f32_e32 v195, v195, v0
	v_exp_f32_e32 v200, v195
	s_nop 0
	v_mul_f32_e32 v173, v173, v200
	v_pk_mul_f32 v[64:65], v[64:65], v[200:201] op_sel_hi:[1,0]
	v_pk_mul_f32 v[62:63], v[62:63], v[200:201] op_sel_hi:[1,0]
	v_pk_mul_f32 v[60:61], v[60:61], v[200:201] op_sel_hi:[1,0]
	v_pk_mul_f32 v[58:59], v[58:59], v[200:201] op_sel_hi:[1,0]
	v_pk_mul_f32 v[56:57], v[56:57], v[200:201] op_sel_hi:[1,0]
	v_pk_mul_f32 v[54:55], v[54:55], v[200:201] op_sel_hi:[1,0]
	v_pk_mul_f32 v[52:53], v[52:53], v[200:201] op_sel_hi:[1,0]
	v_pk_mul_f32 v[50:51], v[50:51], v[200:201] op_sel_hi:[1,0]
	v_pk_mul_f32 v[48:49], v[48:49], v[200:201] op_sel_hi:[1,0]
	v_pk_mul_f32 v[46:47], v[46:47], v[200:201] op_sel_hi:[1,0]
	v_pk_mul_f32 v[44:45], v[44:45], v[200:201] op_sel_hi:[1,0]
	v_pk_mul_f32 v[42:43], v[42:43], v[200:201] op_sel_hi:[1,0]
	v_pk_mul_f32 v[40:41], v[40:41], v[200:201] op_sel_hi:[1,0]
	v_pk_mul_f32 v[38:39], v[38:39], v[200:201] op_sel_hi:[1,0]
	v_pk_mul_f32 v[36:37], v[36:37], v[200:201] op_sel_hi:[1,0]
	v_pk_mul_f32 v[34:35], v[34:35], v[200:201] op_sel_hi:[1,0]
	s_branch .LBB0_451

.LBB0_453:
	s_nop 6
	v_max_f32_e32 v179, v66, v67
	v_max3_f32 v179, v179, v68, v69
	v_max3_f32 v179, v179, v70, v71
	v_max3_f32 v179, v179, v72, v73
	v_max3_f32 v179, v179, v74, v75
	v_max3_f32 v179, v179, v76, v77
	v_max3_f32 v179, v179, v78, v79
	v_max3_f32 v179, v179, v80, v81
	v_mov_b32_e32 v180, v179
	s_nop 1
	v_permlane32_swap_b32_e32 v179, v180
	v_max_f32_e32 v179, v179, v180
	v_mul_f32_e32 v179, 0x3e38aa3b, v179
	v_max_f32_e32 v179, v178, v179
	v_sub_f32_e32 v180, v179, v178
	v_cmp_lt_f32_e32 vcc, s67, v180
	s_cbranch_vccz .LBB0_455
	v_sub_f32_e32 v178, v178, v179
	v_exp_f32_e32 v178, v178
	s_nop 0
	v_mul_f32_e32 v171, v171, v178
	v_pk_mul_f32 v[32:33], v[32:33], v[178:179] op_sel_hi:[1,0]
	v_pk_mul_f32 v[30:31], v[30:31], v[178:179] op_sel_hi:[1,0]
	v_pk_mul_f32 v[28:29], v[28:29], v[178:179] op_sel_hi:[1,0]
	v_pk_mul_f32 v[26:27], v[26:27], v[178:179] op_sel_hi:[1,0]
	v_pk_mul_f32 v[24:25], v[24:25], v[178:179] op_sel_hi:[1,0]
	v_pk_mul_f32 v[22:23], v[22:23], v[178:179] op_sel_hi:[1,0]
	v_pk_mul_f32 v[20:21], v[20:21], v[178:179] op_sel_hi:[1,0]
	v_pk_mul_f32 v[18:19], v[18:19], v[178:179] op_sel_hi:[1,0]
	v_pk_mul_f32 v[16:17], v[16:17], v[178:179] op_sel_hi:[1,0]
	v_pk_mul_f32 v[14:15], v[14:15], v[178:179] op_sel_hi:[1,0]
	v_pk_mul_f32 v[12:13], v[12:13], v[178:179] op_sel_hi:[1,0]
	v_pk_mul_f32 v[10:11], v[10:11], v[178:179] op_sel_hi:[1,0]
	v_pk_mul_f32 v[8:9], v[8:9], v[178:179] op_sel_hi:[1,0]
	v_pk_mul_f32 v[6:7], v[6:7], v[178:179] op_sel_hi:[1,0]
	v_pk_mul_f32 v[4:5], v[4:5], v[178:179] op_sel_hi:[1,0]
	v_pk_mul_f32 v[2:3], v[2:3], v[178:179] op_sel_hi:[1,0]
	s_branch .LBB0_456

.LBB0_467:
	s_nop 10
	v_max_f32_e32 v190, v2, v3
	v_max3_f32 v190, v190, v4, v5
	v_max3_f32 v190, v190, v6, v7
	v_max3_f32 v190, v190, v8, v9
	v_max3_f32 v190, v190, v10, v11
	v_max3_f32 v190, v190, v12, v13
	v_max3_f32 v190, v190, v14, v15
	v_max3_f32 v190, v190, v16, v17
	v_mov_b32_e32 v191, v190
	s_nop 1
	v_permlane32_swap_b32_e32 v190, v191
	v_max_f32_e32 v190, v190, v191
	v_mul_f32_e32 v190, 0x3e38aa3b, v190
	v_max_f32_e32 v191, v153, v153
	v_max_f32_e32 v200, v191, v190
	v_sub_f32_e32 v190, v200, v153
	v_cmp_lt_f32_e32 vcc, s67, v190
	s_cbranch_vccz .LBB0_469
	v_sub_f32_e32 v153, v153, v200
	v_exp_f32_e32 v190, v153
	v_mov_b32_e32 v153, v200
	v_mul_f32_e32 v147, v147, v190
	v_pk_mul_f32 v[64:65], v[64:65], v[190:191] op_sel_hi:[1,0]
	v_pk_mul_f32 v[62:63], v[62:63], v[190:191] op_sel_hi:[1,0]
	v_pk_mul_f32 v[60:61], v[60:61], v[190:191] op_sel_hi:[1,0]
	v_pk_mul_f32 v[58:59], v[58:59], v[190:191] op_sel_hi:[1,0]
	v_pk_mul_f32 v[56:57], v[56:57], v[190:191] op_sel_hi:[1,0]
	v_pk_mul_f32 v[54:55], v[54:55], v[190:191] op_sel_hi:[1,0]
	v_pk_mul_f32 v[52:53], v[52:53], v[190:191] op_sel_hi:[1,0]
	v_pk_mul_f32 v[50:51], v[50:51], v[190:191] op_sel_hi:[1,0]
	v_pk_mul_f32 v[80:81], v[80:81], v[190:191] op_sel_hi:[1,0]
	v_pk_mul_f32 v[78:79], v[78:79], v[190:191] op_sel_hi:[1,0]
	v_pk_mul_f32 v[76:77], v[76:77], v[190:191] op_sel_hi:[1,0]
	v_pk_mul_f32 v[74:75], v[74:75], v[190:191] op_sel_hi:[1,0]
	v_pk_mul_f32 v[72:73], v[72:73], v[190:191] op_sel_hi:[1,0]
	v_pk_mul_f32 v[70:71], v[70:71], v[190:191] op_sel_hi:[1,0]
	v_pk_mul_f32 v[68:69], v[68:69], v[190:191] op_sel_hi:[1,0]
	v_pk_mul_f32 v[66:67], v[66:67], v[190:191] op_sel_hi:[1,0]
	s_branch .LBB0_470

.LBB0_472:
	s_nop 6
	v_max_f32_e32 v0, v2, v3
	v_max3_f32 v0, v0, v4, v5
	v_max3_f32 v0, v0, v6, v7
	v_max3_f32 v0, v0, v8, v9
	v_max3_f32 v0, v0, v10, v11
	v_max3_f32 v0, v0, v12, v13
	v_max3_f32 v0, v0, v14, v15
	v_max3_f32 v0, v0, v16, v17
	v_mov_b32_e32 v176, v0
	s_nop 1
	v_permlane32_swap_b32_e32 v0, v176
	v_max_f32_e32 v0, v0, v176
	v_mul_f32_e32 v0, 0x3e38aa3b, v0
	v_max_f32_e32 v176, v173, v173
	v_max_f32_e32 v201, v176, v0
	v_sub_f32_e32 v0, v201, v173
	v_cmp_lt_f32_e32 vcc, s67, v0
	s_cbranch_vccz .LBB0_474
	v_sub_f32_e32 v0, v173, v201
	v_exp_f32_e32 v0, v0
	v_mov_b32_e32 v173, v201
	v_mul_f32_e32 v146, v146, v0
	v_pk_mul_f32 v[48:49], v[48:49], v[0:1] op_sel_hi:[1,0]
	v_pk_mul_f32 v[46:47], v[46:47], v[0:1] op_sel_hi:[1,0]
	v_pk_mul_f32 v[44:45], v[44:45], v[0:1] op_sel_hi:[1,0]
	v_pk_mul_f32 v[42:43], v[42:43], v[0:1] op_sel_hi:[1,0]
	v_pk_mul_f32 v[40:41], v[40:41], v[0:1] op_sel_hi:[1,0]
	v_pk_mul_f32 v[38:39], v[38:39], v[0:1] op_sel_hi:[1,0]
	v_pk_mul_f32 v[36:37], v[36:37], v[0:1] op_sel_hi:[1,0]
	v_pk_mul_f32 v[34:35], v[34:35], v[0:1] op_sel_hi:[1,0]
	v_pk_mul_f32 v[32:33], v[32:33], v[0:1] op_sel_hi:[1,0]
	v_pk_mul_f32 v[30:31], v[30:31], v[0:1] op_sel_hi:[1,0]
	v_pk_mul_f32 v[28:29], v[28:29], v[0:1] op_sel_hi:[1,0]
	v_pk_mul_f32 v[26:27], v[26:27], v[0:1] op_sel_hi:[1,0]
	v_pk_mul_f32 v[24:25], v[24:25], v[0:1] op_sel_hi:[1,0]
	v_pk_mul_f32 v[22:23], v[22:23], v[0:1] op_sel_hi:[1,0]
	v_pk_mul_f32 v[20:21], v[20:21], v[0:1] op_sel_hi:[1,0]
	v_pk_mul_f32 v[18:19], v[18:19], v[0:1] op_sel_hi:[1,0]
	s_branch .LBB0_475

.LBB0_632:
	s_nop 9
	v_max_f32_e32 v0, v66, v67
	v_max3_f32 v0, v0, v68, v69
	v_max3_f32 v0, v0, v70, v71
	v_max3_f32 v0, v0, v72, v73
	v_max3_f32 v0, v0, v74, v75
	v_max3_f32 v0, v0, v76, v77
	v_max3_f32 v0, v0, v78, v79
	v_max3_f32 v0, v0, v80, v81
	v_cndmask_b32_e64 v0, v248, v0, s[6:7]
	v_mov_b32_e32 v196, v0
	s_nop 1
	v_permlane32_swap_b32_e32 v0, v196
	v_max_f32_e32 v0, v0, v196
	v_mul_f32_e32 v0, 0x3e38aa3b, v0
	v_max_f32_e32 v0, v203, v0
	v_sub_f32_e32 v196, v0, v203
	v_cmp_lt_f32_e32 vcc, s67, v196
	s_cbranch_vccz .LBB0_634
	v_sub_f32_e32 v196, v203, v0
	v_exp_f32_e32 v204, v196
	s_nop 0
	v_mul_f32_e32 v151, v151, v204
	v_pk_mul_f32 v[64:65], v[64:65], v[204:205] op_sel_hi:[1,0]
	v_pk_mul_f32 v[62:63], v[62:63], v[204:205] op_sel_hi:[1,0]
	v_pk_mul_f32 v[60:61], v[60:61], v[204:205] op_sel_hi:[1,0]
	v_pk_mul_f32 v[58:59], v[58:59], v[204:205] op_sel_hi:[1,0]
	v_pk_mul_f32 v[56:57], v[56:57], v[204:205] op_sel_hi:[1,0]
	v_pk_mul_f32 v[54:55], v[54:55], v[204:205] op_sel_hi:[1,0]
	v_pk_mul_f32 v[52:53], v[52:53], v[204:205] op_sel_hi:[1,0]
	v_pk_mul_f32 v[50:51], v[50:51], v[204:205] op_sel_hi:[1,0]
	v_pk_mul_f32 v[48:49], v[48:49], v[204:205] op_sel_hi:[1,0]
	v_pk_mul_f32 v[46:47], v[46:47], v[204:205] op_sel_hi:[1,0]
	v_pk_mul_f32 v[44:45], v[44:45], v[204:205] op_sel_hi:[1,0]
	v_pk_mul_f32 v[42:43], v[42:43], v[204:205] op_sel_hi:[1,0]
	v_pk_mul_f32 v[40:41], v[40:41], v[204:205] op_sel_hi:[1,0]
	v_pk_mul_f32 v[38:39], v[38:39], v[204:205] op_sel_hi:[1,0]
	v_pk_mul_f32 v[36:37], v[36:37], v[204:205] op_sel_hi:[1,0]
	v_pk_mul_f32 v[34:35], v[34:35], v[204:205] op_sel_hi:[1,0]
	s_branch .LBB0_635

.LBB0_637:
	s_nop 6
	v_max_f32_e32 v186, v66, v67
	v_max3_f32 v186, v186, v68, v69
	v_max3_f32 v186, v186, v70, v71
	v_max3_f32 v186, v186, v72, v73
	v_max3_f32 v186, v186, v74, v75
	v_max3_f32 v186, v186, v76, v77
	v_max3_f32 v186, v186, v78, v79
	v_max3_f32 v186, v186, v80, v81
	v_cndmask_b32_e64 v186, v248, v186, s[4:5]
	v_mov_b32_e32 v187, v186
	s_nop 1
	v_permlane32_swap_b32_e32 v186, v187
	v_max_f32_e32 v186, v186, v187
	v_mul_f32_e32 v186, 0x3e38aa3b, v186
	v_max_f32_e32 v186, v185, v186
	v_sub_f32_e32 v187, v186, v185
	v_cmp_lt_f32_e32 vcc, s67, v187
	s_cbranch_vccz .LBB0_639
	v_sub_f32_e32 v185, v185, v186
	v_exp_f32_e32 v188, v185
	s_nop 0
	v_mul_f32_e32 v150, v150, v188
	v_pk_mul_f32 v[32:33], v[32:33], v[188:189] op_sel_hi:[1,0]
	v_pk_mul_f32 v[30:31], v[30:31], v[188:189] op_sel_hi:[1,0]
	v_pk_mul_f32 v[28:29], v[28:29], v[188:189] op_sel_hi:[1,0]
	v_pk_mul_f32 v[26:27], v[26:27], v[188:189] op_sel_hi:[1,0]
	v_pk_mul_f32 v[24:25], v[24:25], v[188:189] op_sel_hi:[1,0]
	v_pk_mul_f32 v[22:23], v[22:23], v[188:189] op_sel_hi:[1,0]
	v_pk_mul_f32 v[20:21], v[20:21], v[188:189] op_sel_hi:[1,0]
	v_pk_mul_f32 v[18:19], v[18:19], v[188:189] op_sel_hi:[1,0]
	v_pk_mul_f32 v[16:17], v[16:17], v[188:189] op_sel_hi:[1,0]
	v_pk_mul_f32 v[14:15], v[14:15], v[188:189] op_sel_hi:[1,0]
	v_pk_mul_f32 v[12:13], v[12:13], v[188:189] op_sel_hi:[1,0]
	v_pk_mul_f32 v[10:11], v[10:11], v[188:189] op_sel_hi:[1,0]
	v_pk_mul_f32 v[8:9], v[8:9], v[188:189] op_sel_hi:[1,0]
	v_pk_mul_f32 v[6:7], v[6:7], v[188:189] op_sel_hi:[1,0]
	v_pk_mul_f32 v[4:5], v[4:5], v[188:189] op_sel_hi:[1,0]
	v_pk_mul_f32 v[2:3], v[2:3], v[188:189] op_sel_hi:[1,0]
	s_branch .LBB0_640

.LBB0_646:
	s_nop 9
	v_max_f32_e32 v0, v66, v67
	v_max3_f32 v0, v0, v68, v69
	v_max3_f32 v0, v0, v70, v71
	v_max3_f32 v0, v0, v72, v73
	v_max3_f32 v0, v0, v74, v75
	v_max3_f32 v0, v0, v76, v77
	v_max3_f32 v0, v0, v78, v79
	v_max3_f32 v0, v0, v80, v81
	v_mov_b32_e32 v196, v0
	s_nop 1
	v_permlane32_swap_b32_e32 v0, v196
	v_max_f32_e32 v0, v0, v196
	v_mul_f32_e32 v0, 0x3e38aa3b, v0
	v_max_f32_e32 v0, v202, v0
	v_sub_f32_e32 v196, v0, v202
	v_cmp_lt_f32_e32 vcc, s67, v196
	s_cbranch_vccz .LBB0_648
	v_sub_f32_e32 v196, v202, v0
	v_exp_f32_e32 v202, v196
	s_nop 0
	v_mul_f32_e32 v147, v147, v202
	v_pk_mul_f32 v[64:65], v[64:65], v[202:203] op_sel_hi:[1,0]
	v_pk_mul_f32 v[62:63], v[62:63], v[202:203] op_sel_hi:[1,0]
	v_pk_mul_f32 v[60:61], v[60:61], v[202:203] op_sel_hi:[1,0]
	v_pk_mul_f32 v[58:59], v[58:59], v[202:203] op_sel_hi:[1,0]
	v_pk_mul_f32 v[56:57], v[56:57], v[202:203] op_sel_hi:[1,0]
	v_pk_mul_f32 v[54:55], v[54:55], v[202:203] op_sel_hi:[1,0]
	v_pk_mul_f32 v[52:53], v[52:53], v[202:203] op_sel_hi:[1,0]
	v_pk_mul_f32 v[50:51], v[50:51], v[202:203] op_sel_hi:[1,0]
	v_pk_mul_f32 v[48:49], v[48:49], v[202:203] op_sel_hi:[1,0]
	v_pk_mul_f32 v[46:47], v[46:47], v[202:203] op_sel_hi:[1,0]
	v_pk_mul_f32 v[44:45], v[44:45], v[202:203] op_sel_hi:[1,0]
	v_pk_mul_f32 v[42:43], v[42:43], v[202:203] op_sel_hi:[1,0]
	v_pk_mul_f32 v[40:41], v[40:41], v[202:203] op_sel_hi:[1,0]
	v_pk_mul_f32 v[38:39], v[38:39], v[202:203] op_sel_hi:[1,0]
	v_pk_mul_f32 v[36:37], v[36:37], v[202:203] op_sel_hi:[1,0]
	v_pk_mul_f32 v[34:35], v[34:35], v[202:203] op_sel_hi:[1,0]
	s_branch .LBB0_649

.LBB0_651:
	s_nop 6
	v_max_f32_e32 v181, v66, v67
	v_max3_f32 v181, v181, v68, v69
	v_max3_f32 v181, v181, v70, v71
	v_max3_f32 v181, v181, v72, v73
	v_max3_f32 v181, v181, v74, v75
	v_max3_f32 v181, v181, v76, v77
	v_max3_f32 v181, v181, v78, v79
	v_max3_f32 v181, v181, v80, v81
	v_mov_b32_e32 v182, v181
	s_nop 1
	v_permlane32_swap_b32_e32 v181, v182
	v_max_f32_e32 v181, v181, v182
	v_mul_f32_e32 v181, 0x3e38aa3b, v181
	v_max_f32_e32 v181, v180, v181
	v_sub_f32_e32 v182, v181, v180
	v_cmp_lt_f32_e32 vcc, s67, v182
	s_cbranch_vccz .LBB0_653
	v_sub_f32_e32 v180, v180, v181
	v_exp_f32_e32 v180, v180
	s_nop 0
	v_mul_f32_e32 v146, v146, v180
	v_pk_mul_f32 v[32:33], v[32:33], v[180:181] op_sel_hi:[1,0]
	v_pk_mul_f32 v[30:31], v[30:31], v[180:181] op_sel_hi:[1,0]
	v_pk_mul_f32 v[28:29], v[28:29], v[180:181] op_sel_hi:[1,0]
	v_pk_mul_f32 v[26:27], v[26:27], v[180:181] op_sel_hi:[1,0]
	v_pk_mul_f32 v[24:25], v[24:25], v[180:181] op_sel_hi:[1,0]
	v_pk_mul_f32 v[22:23], v[22:23], v[180:181] op_sel_hi:[1,0]
	v_pk_mul_f32 v[20:21], v[20:21], v[180:181] op_sel_hi:[1,0]
	v_pk_mul_f32 v[18:19], v[18:19], v[180:181] op_sel_hi:[1,0]
	v_pk_mul_f32 v[16:17], v[16:17], v[180:181] op_sel_hi:[1,0]
	v_pk_mul_f32 v[14:15], v[14:15], v[180:181] op_sel_hi:[1,0]
	v_pk_mul_f32 v[12:13], v[12:13], v[180:181] op_sel_hi:[1,0]
	v_pk_mul_f32 v[10:11], v[10:11], v[180:181] op_sel_hi:[1,0]
	v_pk_mul_f32 v[8:9], v[8:9], v[180:181] op_sel_hi:[1,0]
	v_pk_mul_f32 v[6:7], v[6:7], v[180:181] op_sel_hi:[1,0]
	v_pk_mul_f32 v[4:5], v[4:5], v[180:181] op_sel_hi:[1,0]
	v_pk_mul_f32 v[2:3], v[2:3], v[180:181] op_sel_hi:[1,0]
	s_branch .LBB0_654
